# residual epilogues: cross-row sum-of-squares reduction via v_permlane16/32_swap instead of two ds_bpermute round trips per row group
# baseline (speedup 1.0000x reference)
; __device__ __forceinline__ float sumsq8(f32x4 a, f32x4 b) { return (a.x * a.x + a.y * a.y) + (a.z * a.z + a.w * a.w) + (b.x * b.x + b.y * b.y) + (b.z * b.z + b.w * b.w); }
.LBB0_1725:
	v_pk_mul_f32 v[116:117], v[116:117], v[116:117]
	v_pk_mul_f32 v[118:119], v[118:119], v[118:119]
	v_pk_mul_f32 v[112:113], v[112:113], v[112:113]
	v_add_f32_e32 v118, v118, v119
	v_add_f32_e32 v116, v116, v117
	v_pk_mul_f32 v[114:115], v[114:115], v[114:115]
	v_add_f32_e32 v116, v116, v118
	v_add_f32_e32 v112, v112, v113
	v_pk_mul_f32 v[124:125], v[124:125], v[124:125]
	v_pk_mul_f32 v[126:127], v[126:127], v[126:127]
	v_add_f32_e32 v112, v112, v116
	v_add_f32_e32 v113, v114, v115
	v_pk_mul_f32 v[120:121], v[120:121], v[120:121]
	v_add_f32_e32 v112, v113, v112
	v_add_f32_e32 v113, v126, v127
	v_add_f32_e32 v114, v124, v125
	v_pk_mul_f32 v[122:123], v[122:123], v[122:123]
	v_add_f32_e32 v113, v114, v113
	v_add_f32_e32 v114, v120, v121
	v_add_f32_e32 v113, v114, v113
	v_add_f32_e32 v114, v122, v123
	v_add_f32_e32 v113, v114, v113
	v_add_f32_e32 v112, v113, v112
	v_mov_b32_e32 v113, v112
	s_nop 1
	v_permlane16_swap_b32_e32 v113, v112
	s_lshl_b32 s34, s42, 2
	s_ashr_i32 s35, s34, 31
	s_waitcnt lgkmcnt(0)
	v_add_f32_e32 v112, v112, v113
	v_mov_b32_e32 v113, v112
	s_nop 1
	v_permlane32_swap_b32_e32 v113, v112
	s_and_saveexec_b64 s[44:45], s[26:27]
	s_cbranch_execz .LBB0_1727
	v_readlane_b32 s50, v254, 8
	v_lshlrev_b64 v[114:115], 6, v[140:141]
	v_readlane_b32 s51, v254, 9
	s_lshl_b32 s42, s92, 2
	s_waitcnt lgkmcnt(0)
	v_add_f32_e32 v112, v112, v113
	v_lshl_add_u64 v[114:115], s[50:51], 0, v[114:115]
	v_lshl_add_u64 v[114:115], s[34:35], 2, v[114:115]
	v_lshl_add_u64 v[114:115], v[114:115], 0, s[42:43]
	global_store_dword v[114:115], v112, off

; __device__ __forceinline__ float sumsq8(f32x4 a, f32x4 b) { return (a.x * a.x + a.y * a.y) + (a.z * a.z + a.w * a.w) + (b.x * b.x + b.y * b.y) + (b.z * b.z + b.w * b.w); }
.LBB0_1731:
	v_pk_mul_f32 v[100:101], v[100:101], v[100:101]
	v_pk_mul_f32 v[102:103], v[102:103], v[102:103]
	v_pk_mul_f32 v[96:97], v[96:97], v[96:97]
	v_add_f32_e32 v102, v102, v103
	v_add_f32_e32 v100, v100, v101
	v_pk_mul_f32 v[98:99], v[98:99], v[98:99]
	v_add_f32_e32 v100, v100, v102
	v_add_f32_e32 v96, v96, v97
	v_pk_mul_f32 v[108:109], v[108:109], v[108:109]
	v_pk_mul_f32 v[110:111], v[110:111], v[110:111]
	v_add_f32_e32 v96, v96, v100
	v_add_f32_e32 v97, v98, v99
	v_pk_mul_f32 v[104:105], v[104:105], v[104:105]
	v_add_f32_e32 v96, v97, v96
	v_add_f32_e32 v97, v110, v111
	v_add_f32_e32 v98, v108, v109
	v_pk_mul_f32 v[106:107], v[106:107], v[106:107]
	v_add_f32_e32 v97, v98, v97
	v_add_f32_e32 v98, v104, v105
	v_add_f32_e32 v97, v98, v97
	v_add_f32_e32 v98, v106, v107
	v_add_f32_e32 v97, v98, v97
	v_add_f32_e32 v96, v97, v96
	v_mov_b32_e32 v97, v96
	s_nop 1
	v_permlane16_swap_b32_e32 v97, v96
	s_waitcnt lgkmcnt(0)
	v_add_f32_e32 v96, v96, v97
	v_mov_b32_e32 v97, v96
	s_nop 1
	v_permlane32_swap_b32_e32 v97, v96
	s_and_saveexec_b64 s[44:45], s[26:27]
	s_cbranch_execz .LBB0_1733
	v_readlane_b32 s50, v254, 8
	v_lshlrev_b64 v[98:99], 6, v[112:113]
	v_readlane_b32 s51, v254, 9
	s_lshl_b32 s42, s92, 2
	s_waitcnt lgkmcnt(0)
	v_add_f32_e32 v96, v96, v97
	v_lshl_add_u64 v[98:99], s[50:51], 0, v[98:99]
	v_lshl_add_u64 v[98:99], s[34:35], 2, v[98:99]
	v_lshl_add_u64 v[98:99], v[98:99], 0, s[42:43]
	global_store_dword v[98:99], v96, off

; __device__ __forceinline__ float sumsq8(f32x4 a, f32x4 b) { return (a.x * a.x + a.y * a.y) + (a.z * a.z + a.w * a.w) + (b.x * b.x + b.y * b.y) + (b.z * b.z + b.w * b.w); }
.LBB0_1737:
	v_pk_mul_f32 v[84:85], v[84:85], v[84:85]
	v_pk_mul_f32 v[86:87], v[86:87], v[86:87]
	v_pk_mul_f32 v[80:81], v[80:81], v[80:81]
	v_add_f32_e32 v86, v86, v87
	v_add_f32_e32 v84, v84, v85
	v_pk_mul_f32 v[82:83], v[82:83], v[82:83]
	v_add_f32_e32 v84, v84, v86
	v_add_f32_e32 v80, v80, v81
	v_pk_mul_f32 v[92:93], v[92:93], v[92:93]
	v_pk_mul_f32 v[94:95], v[94:95], v[94:95]
	v_add_f32_e32 v80, v80, v84
	v_add_f32_e32 v81, v82, v83
	v_pk_mul_f32 v[88:89], v[88:89], v[88:89]
	v_add_f32_e32 v80, v81, v80
	v_add_f32_e32 v81, v94, v95
	v_add_f32_e32 v82, v92, v93
	v_pk_mul_f32 v[90:91], v[90:91], v[90:91]
	v_add_f32_e32 v81, v82, v81
	v_add_f32_e32 v82, v88, v89
	v_add_f32_e32 v81, v82, v81
	v_add_f32_e32 v82, v90, v91
	v_add_f32_e32 v81, v82, v81
	v_add_f32_e32 v80, v81, v80
	v_mov_b32_e32 v81, v80
	s_nop 1
	v_permlane16_swap_b32_e32 v81, v80
	s_waitcnt lgkmcnt(0)
	v_add_f32_e32 v80, v80, v81
	v_mov_b32_e32 v81, v80
	s_nop 1
	v_permlane32_swap_b32_e32 v81, v80
	s_and_saveexec_b64 s[44:45], s[26:27]
	s_cbranch_execz .LBB0_1739
	v_readlane_b32 s50, v254, 8
	v_lshlrev_b64 v[82:83], 6, v[96:97]
	v_readlane_b32 s51, v254, 9
	s_lshl_b32 s42, s92, 2
	s_waitcnt lgkmcnt(0)
	v_add_f32_e32 v80, v80, v81
	v_lshl_add_u64 v[82:83], s[50:51], 0, v[82:83]
	v_lshl_add_u64 v[82:83], s[34:35], 2, v[82:83]
	v_lshl_add_u64 v[82:83], v[82:83], 0, s[42:43]
	global_store_dword v[82:83], v80, off

; __device__ __forceinline__ float sumsq8(f32x4 a, f32x4 b) { return (a.x * a.x + a.y * a.y) + (a.z * a.z + a.w * a.w) + (b.x * b.x + b.y * b.y) + (b.z * b.z + b.w * b.w); }
.LBB0_1743:
	v_pk_mul_f32 v[68:69], v[68:69], v[68:69]
	v_pk_mul_f32 v[70:71], v[70:71], v[70:71]
	v_pk_mul_f32 v[64:65], v[64:65], v[64:65]
	v_add_f32_e32 v70, v70, v71
	v_add_f32_e32 v68, v68, v69
	v_pk_mul_f32 v[66:67], v[66:67], v[66:67]
	v_add_f32_e32 v68, v68, v70
	v_add_f32_e32 v64, v64, v65
	v_pk_mul_f32 v[76:77], v[76:77], v[76:77]
	v_pk_mul_f32 v[78:79], v[78:79], v[78:79]
	v_add_f32_e32 v64, v64, v68
	v_add_f32_e32 v65, v66, v67
	v_pk_mul_f32 v[72:73], v[72:73], v[72:73]
	v_add_f32_e32 v64, v65, v64
	v_add_f32_e32 v65, v78, v79
	v_add_f32_e32 v66, v76, v77
	v_pk_mul_f32 v[74:75], v[74:75], v[74:75]
	v_add_f32_e32 v65, v66, v65
	v_add_f32_e32 v66, v72, v73
	v_add_f32_e32 v65, v66, v65
	v_add_f32_e32 v66, v74, v75
	v_add_f32_e32 v65, v66, v65
	v_add_f32_e32 v64, v65, v64
	v_mov_b32_e32 v65, v64
	s_nop 1
	v_permlane16_swap_b32_e32 v65, v64
	s_waitcnt lgkmcnt(0)
	v_add_f32_e32 v64, v64, v65
	v_mov_b32_e32 v65, v64
	s_nop 1
	v_permlane32_swap_b32_e32 v65, v64
	s_and_saveexec_b64 s[44:45], s[26:27]
	s_cbranch_execz .LBB0_1745
	v_readlane_b32 s50, v254, 8
	v_lshlrev_b64 v[66:67], 6, v[80:81]
	v_readlane_b32 s51, v254, 9
	s_lshl_b32 s42, s92, 2
	s_waitcnt lgkmcnt(0)
	v_add_f32_e32 v64, v64, v65
	v_lshl_add_u64 v[66:67], s[50:51], 0, v[66:67]
	v_lshl_add_u64 v[66:67], s[34:35], 2, v[66:67]
	v_lshl_add_u64 v[66:67], v[66:67], 0, s[42:43]
	global_store_dword v[66:67], v64, off

; __device__ __forceinline__ float sumsq8(f32x4 a, f32x4 b) { return (a.x * a.x + a.y * a.y) + (a.z * a.z + a.w * a.w) + (b.x * b.x + b.y * b.y) + (b.z * b.z + b.w * b.w); }
.LBB0_1749:
	v_pk_mul_f32 v[52:53], v[52:53], v[52:53]
	v_pk_mul_f32 v[54:55], v[54:55], v[54:55]
	v_pk_mul_f32 v[48:49], v[48:49], v[48:49]
	v_add_f32_e32 v54, v54, v55
	v_add_f32_e32 v52, v52, v53
	v_pk_mul_f32 v[50:51], v[50:51], v[50:51]
	v_add_f32_e32 v52, v52, v54
	v_add_f32_e32 v48, v48, v49
	v_pk_mul_f32 v[60:61], v[60:61], v[60:61]
	v_pk_mul_f32 v[62:63], v[62:63], v[62:63]
	v_add_f32_e32 v48, v48, v52
	v_add_f32_e32 v49, v50, v51
	v_pk_mul_f32 v[56:57], v[56:57], v[56:57]
	v_add_f32_e32 v48, v49, v48
	v_add_f32_e32 v49, v62, v63
	v_add_f32_e32 v50, v60, v61
	v_pk_mul_f32 v[58:59], v[58:59], v[58:59]
	v_add_f32_e32 v49, v50, v49
	v_add_f32_e32 v50, v56, v57
	v_add_f32_e32 v49, v50, v49
	v_add_f32_e32 v50, v58, v59
	v_add_f32_e32 v49, v50, v49
	v_add_f32_e32 v48, v49, v48
	v_mov_b32_e32 v49, v48
	s_nop 1
	v_permlane16_swap_b32_e32 v49, v48
	s_waitcnt lgkmcnt(0)
	v_add_f32_e32 v48, v48, v49
	v_mov_b32_e32 v49, v48
	s_nop 1
	v_permlane32_swap_b32_e32 v49, v48
	s_and_saveexec_b64 s[44:45], s[26:27]
	s_cbranch_execz .LBB0_1751
	v_readlane_b32 s50, v254, 8
	v_lshlrev_b64 v[50:51], 6, v[64:65]
	v_readlane_b32 s51, v254, 9
	s_lshl_b32 s42, s92, 2
	s_waitcnt lgkmcnt(0)
	v_add_f32_e32 v48, v48, v49
	v_lshl_add_u64 v[50:51], s[50:51], 0, v[50:51]
	v_lshl_add_u64 v[50:51], s[34:35], 2, v[50:51]
	v_lshl_add_u64 v[50:51], v[50:51], 0, s[42:43]
	global_store_dword v[50:51], v48, off

; __device__ __forceinline__ float sumsq8(f32x4 a, f32x4 b) { return (a.x * a.x + a.y * a.y) + (a.z * a.z + a.w * a.w) + (b.x * b.x + b.y * b.y) + (b.z * b.z + b.w * b.w); }
.LBB0_1755:
	v_pk_mul_f32 v[36:37], v[36:37], v[36:37]
	v_pk_mul_f32 v[38:39], v[38:39], v[38:39]
	v_pk_mul_f32 v[32:33], v[32:33], v[32:33]
	v_add_f32_e32 v38, v38, v39
	v_add_f32_e32 v36, v36, v37
	v_pk_mul_f32 v[34:35], v[34:35], v[34:35]
	v_add_f32_e32 v36, v36, v38
	v_add_f32_e32 v32, v32, v33
	v_pk_mul_f32 v[44:45], v[44:45], v[44:45]
	v_pk_mul_f32 v[46:47], v[46:47], v[46:47]
	v_add_f32_e32 v32, v32, v36
	v_add_f32_e32 v33, v34, v35
	v_pk_mul_f32 v[40:41], v[40:41], v[40:41]
	v_add_f32_e32 v32, v33, v32
	v_add_f32_e32 v33, v46, v47
	v_add_f32_e32 v34, v44, v45
	v_pk_mul_f32 v[42:43], v[42:43], v[42:43]
	v_add_f32_e32 v33, v34, v33
	v_add_f32_e32 v34, v40, v41
	v_add_f32_e32 v33, v34, v33
	v_add_f32_e32 v34, v42, v43
	v_add_f32_e32 v33, v34, v33
	v_add_f32_e32 v32, v33, v32
	v_mov_b32_e32 v33, v32
	s_nop 1
	v_permlane16_swap_b32_e32 v33, v32
	s_waitcnt lgkmcnt(0)
	v_add_f32_e32 v32, v32, v33
	v_mov_b32_e32 v33, v32
	s_nop 1
	v_permlane32_swap_b32_e32 v33, v32
	s_and_saveexec_b64 s[44:45], s[26:27]
	s_cbranch_execz .LBB0_1757
	v_readlane_b32 s50, v254, 8
	v_lshlrev_b64 v[34:35], 6, v[48:49]
	v_readlane_b32 s51, v254, 9
	s_lshl_b32 s42, s92, 2
	s_waitcnt lgkmcnt(0)
	v_add_f32_e32 v32, v32, v33
	v_lshl_add_u64 v[34:35], s[50:51], 0, v[34:35]
	v_lshl_add_u64 v[34:35], s[34:35], 2, v[34:35]
	v_lshl_add_u64 v[34:35], v[34:35], 0, s[42:43]
	global_store_dword v[34:35], v32, off

; __device__ __forceinline__ float sumsq8(f32x4 a, f32x4 b) { return (a.x * a.x + a.y * a.y) + (a.z * a.z + a.w * a.w) + (b.x * b.x + b.y * b.y) + (b.z * b.z + b.w * b.w); }
.LBB0_1761:
	v_pk_mul_f32 v[20:21], v[20:21], v[20:21]
	v_pk_mul_f32 v[22:23], v[22:23], v[22:23]
	v_pk_mul_f32 v[16:17], v[16:17], v[16:17]
	v_add_f32_e32 v22, v22, v23
	v_add_f32_e32 v20, v20, v21
	v_pk_mul_f32 v[18:19], v[18:19], v[18:19]
	v_add_f32_e32 v20, v20, v22
	v_add_f32_e32 v16, v16, v17
	v_pk_mul_f32 v[28:29], v[28:29], v[28:29]
	v_pk_mul_f32 v[30:31], v[30:31], v[30:31]
	v_add_f32_e32 v16, v16, v20
	v_add_f32_e32 v17, v18, v19
	v_pk_mul_f32 v[24:25], v[24:25], v[24:25]
	v_add_f32_e32 v16, v17, v16
	v_add_f32_e32 v17, v30, v31
	v_add_f32_e32 v18, v28, v29
	v_pk_mul_f32 v[26:27], v[26:27], v[26:27]
	v_add_f32_e32 v17, v18, v17
	v_add_f32_e32 v18, v24, v25
	v_add_f32_e32 v17, v18, v17
	v_add_f32_e32 v18, v26, v27
	v_add_f32_e32 v17, v18, v17
	v_add_f32_e32 v16, v17, v16
	v_mov_b32_e32 v17, v16
	s_nop 1
	v_permlane16_swap_b32_e32 v17, v16
	s_waitcnt lgkmcnt(0)
	v_add_f32_e32 v16, v16, v17
	v_mov_b32_e32 v17, v16
	s_nop 1
	v_permlane32_swap_b32_e32 v17, v16
	s_and_saveexec_b64 s[44:45], s[26:27]
	s_cbranch_execz .LBB0_1763
	v_readlane_b32 s50, v254, 8
	v_lshlrev_b64 v[18:19], 6, v[32:33]
	v_readlane_b32 s51, v254, 9
	s_lshl_b32 s42, s92, 2
	s_waitcnt lgkmcnt(0)
	v_add_f32_e32 v16, v16, v17
	v_lshl_add_u64 v[18:19], s[50:51], 0, v[18:19]
	v_lshl_add_u64 v[18:19], s[34:35], 2, v[18:19]
	v_lshl_add_u64 v[18:19], v[18:19], 0, s[42:43]
	global_store_dword v[18:19], v16, off

; __device__ __forceinline__ float sumsq8(f32x4 a, f32x4 b) { return (a.x * a.x + a.y * a.y) + (a.z * a.z + a.w * a.w) + (b.x * b.x + b.y * b.y) + (b.z * b.z + b.w * b.w); }
.LBB0_1767:
	v_pk_mul_f32 v[4:5], v[4:5], v[4:5]
	v_pk_mul_f32 v[6:7], v[6:7], v[6:7]
	v_pk_mul_f32 v[0:1], v[0:1], v[0:1]
	v_add_f32_e32 v6, v6, v7
	v_add_f32_e32 v4, v4, v5
	v_pk_mul_f32 v[2:3], v[2:3], v[2:3]
	v_add_f32_e32 v4, v4, v6
	v_add_f32_e32 v0, v0, v1
	v_pk_mul_f32 v[12:13], v[12:13], v[12:13]
	v_pk_mul_f32 v[14:15], v[14:15], v[14:15]
	v_add_f32_e32 v0, v0, v4
	v_add_f32_e32 v1, v2, v3
	v_pk_mul_f32 v[8:9], v[8:9], v[8:9]
	v_add_f32_e32 v0, v1, v0
	v_add_f32_e32 v1, v14, v15
	v_add_f32_e32 v2, v12, v13
	v_pk_mul_f32 v[10:11], v[10:11], v[10:11]
	v_add_f32_e32 v1, v2, v1
	v_add_f32_e32 v2, v8, v9
	v_add_f32_e32 v1, v2, v1
	v_add_f32_e32 v2, v10, v11
	v_add_f32_e32 v1, v2, v1
	v_add_f32_e32 v0, v1, v0
	v_mov_b32_e32 v1, v0
	s_nop 1
	v_permlane16_swap_b32_e32 v1, v0
	s_waitcnt lgkmcnt(0)
	v_add_f32_e32 v0, v0, v1
	v_mov_b32_e32 v1, v0
	s_nop 1
	v_permlane32_swap_b32_e32 v1, v0
	s_and_saveexec_b64 s[4:5], s[26:27]
	s_cbranch_execz .LBB0_1769
	v_readlane_b32 s44, v254, 8
	v_lshlrev_b64 v[2:3], 6, v[16:17]
	v_readlane_b32 s45, v254, 9
	s_lshl_b32 s42, s92, 2
	s_waitcnt lgkmcnt(0)
	v_add_f32_e32 v0, v0, v1
	v_lshl_add_u64 v[2:3], s[44:45], 0, v[2:3]
	v_lshl_add_u64 v[2:3], s[34:35], 2, v[2:3]
	v_lshl_add_u64 v[2:3], v[2:3], 0, s[42:43]
	global_store_dword v[2:3], v0, off

; __device__ __forceinline__ float sumsq8(f32x4 a, f32x4 b) { return (a.x * a.x + a.y * a.y) + (a.z * a.z + a.w * a.w) + (b.x * b.x + b.y * b.y) + (b.z * b.z + b.w * b.w); }
.LBB0_2977:
	v_pk_mul_f32 v[116:117], v[116:117], v[116:117]
	v_pk_mul_f32 v[118:119], v[118:119], v[118:119]
	v_pk_mul_f32 v[112:113], v[112:113], v[112:113]
	v_add_f32_e32 v118, v118, v119
	v_add_f32_e32 v116, v116, v117
	v_pk_mul_f32 v[114:115], v[114:115], v[114:115]
	v_add_f32_e32 v116, v116, v118
	v_add_f32_e32 v112, v112, v113
	v_pk_mul_f32 v[124:125], v[124:125], v[124:125]
	v_pk_mul_f32 v[126:127], v[126:127], v[126:127]
	v_add_f32_e32 v112, v112, v116
	v_add_f32_e32 v113, v114, v115
	v_pk_mul_f32 v[120:121], v[120:121], v[120:121]
	v_add_f32_e32 v112, v113, v112
	v_add_f32_e32 v113, v126, v127
	v_add_f32_e32 v114, v124, v125
	v_pk_mul_f32 v[122:123], v[122:123], v[122:123]
	v_add_f32_e32 v113, v114, v113
	v_add_f32_e32 v114, v120, v121
	v_add_f32_e32 v113, v114, v113
	v_add_f32_e32 v114, v122, v123
	v_add_f32_e32 v113, v114, v113
	v_add_f32_e32 v112, v113, v112
	v_mov_b32_e32 v113, v112
	s_nop 1
	v_permlane16_swap_b32_e32 v113, v112
	s_lshl_b32 s56, s42, 2
	s_ashr_i32 s57, s56, 31
	s_waitcnt lgkmcnt(0)
	v_add_f32_e32 v112, v112, v113
	v_mov_b32_e32 v113, v112
	s_nop 1
	v_permlane32_swap_b32_e32 v113, v112
	s_and_saveexec_b64 s[46:47], s[28:29]
	s_cbranch_execz .LBB0_2979
	v_readlane_b32 s48, v254, 8
	v_lshlrev_b64 v[114:115], 6, v[140:141]
	v_readlane_b32 s49, v254, 9
	s_lshl_b32 s42, s18, 2
	s_waitcnt lgkmcnt(0)
	v_add_f32_e32 v112, v112, v113
	v_lshl_add_u64 v[114:115], s[48:49], 0, v[114:115]
	v_lshl_add_u64 v[114:115], s[56:57], 2, v[114:115]
	v_lshl_add_u64 v[114:115], v[114:115], 0, s[42:43]
	global_store_dword v[114:115], v112, off

; __device__ __forceinline__ float sumsq8(f32x4 a, f32x4 b) { return (a.x * a.x + a.y * a.y) + (a.z * a.z + a.w * a.w) + (b.x * b.x + b.y * b.y) + (b.z * b.z + b.w * b.w); }
.LBB0_2987:
	v_pk_mul_f32 v[100:101], v[100:101], v[100:101]
	v_pk_mul_f32 v[102:103], v[102:103], v[102:103]
	v_pk_mul_f32 v[96:97], v[96:97], v[96:97]
	v_add_f32_e32 v102, v102, v103
	v_add_f32_e32 v100, v100, v101
	v_pk_mul_f32 v[98:99], v[98:99], v[98:99]
	v_add_f32_e32 v100, v100, v102
	v_add_f32_e32 v96, v96, v97
	v_pk_mul_f32 v[108:109], v[108:109], v[108:109]
	v_pk_mul_f32 v[110:111], v[110:111], v[110:111]
	v_add_f32_e32 v96, v96, v100
	v_add_f32_e32 v97, v98, v99
	v_pk_mul_f32 v[104:105], v[104:105], v[104:105]
	v_add_f32_e32 v96, v97, v96
	v_add_f32_e32 v97, v110, v111
	v_add_f32_e32 v98, v108, v109
	v_pk_mul_f32 v[106:107], v[106:107], v[106:107]
	v_add_f32_e32 v97, v98, v97
	v_add_f32_e32 v98, v104, v105
	v_add_f32_e32 v97, v98, v97
	v_add_f32_e32 v98, v106, v107
	v_add_f32_e32 v97, v98, v97
	v_add_f32_e32 v96, v97, v96
	v_mov_b32_e32 v97, v96
	s_nop 1
	v_permlane16_swap_b32_e32 v97, v96
	s_waitcnt lgkmcnt(0)
	v_add_f32_e32 v96, v96, v97
	v_mov_b32_e32 v97, v96
	s_nop 1
	v_permlane32_swap_b32_e32 v97, v96
	s_and_saveexec_b64 s[46:47], s[28:29]
	s_cbranch_execz .LBB0_2989
	v_readlane_b32 s48, v254, 8
	v_lshlrev_b64 v[98:99], 6, v[112:113]
	v_readlane_b32 s49, v254, 9
	s_lshl_b32 s42, s18, 2
	s_waitcnt lgkmcnt(0)
	v_add_f32_e32 v96, v96, v97
	v_lshl_add_u64 v[98:99], s[48:49], 0, v[98:99]
	v_lshl_add_u64 v[98:99], s[56:57], 2, v[98:99]
	v_lshl_add_u64 v[98:99], v[98:99], 0, s[42:43]
	global_store_dword v[98:99], v96, off

; __device__ __forceinline__ float sumsq8(f32x4 a, f32x4 b) { return (a.x * a.x + a.y * a.y) + (a.z * a.z + a.w * a.w) + (b.x * b.x + b.y * b.y) + (b.z * b.z + b.w * b.w); }
.LBB0_2997:
	v_pk_mul_f32 v[84:85], v[84:85], v[84:85]
	v_pk_mul_f32 v[86:87], v[86:87], v[86:87]
	v_pk_mul_f32 v[80:81], v[80:81], v[80:81]
	v_add_f32_e32 v86, v86, v87
	v_add_f32_e32 v84, v84, v85
	v_pk_mul_f32 v[82:83], v[82:83], v[82:83]
	v_add_f32_e32 v84, v84, v86
	v_add_f32_e32 v80, v80, v81
	v_pk_mul_f32 v[92:93], v[92:93], v[92:93]
	v_pk_mul_f32 v[94:95], v[94:95], v[94:95]
	v_add_f32_e32 v80, v80, v84
	v_add_f32_e32 v81, v82, v83
	v_pk_mul_f32 v[88:89], v[88:89], v[88:89]
	v_add_f32_e32 v80, v81, v80
	v_add_f32_e32 v81, v94, v95
	v_add_f32_e32 v82, v92, v93
	v_pk_mul_f32 v[90:91], v[90:91], v[90:91]
	v_add_f32_e32 v81, v82, v81
	v_add_f32_e32 v82, v88, v89
	v_add_f32_e32 v81, v82, v81
	v_add_f32_e32 v82, v90, v91
	v_add_f32_e32 v81, v82, v81
	v_add_f32_e32 v80, v81, v80
	v_mov_b32_e32 v81, v80
	s_nop 1
	v_permlane16_swap_b32_e32 v81, v80
	s_waitcnt lgkmcnt(0)
	v_add_f32_e32 v80, v80, v81
	v_mov_b32_e32 v81, v80
	s_nop 1
	v_permlane32_swap_b32_e32 v81, v80
	s_and_saveexec_b64 s[46:47], s[28:29]
	s_cbranch_execz .LBB0_2999
	v_readlane_b32 s48, v254, 8
	v_lshlrev_b64 v[82:83], 6, v[96:97]
	v_readlane_b32 s49, v254, 9
	s_lshl_b32 s42, s18, 2
	s_waitcnt lgkmcnt(0)
	v_add_f32_e32 v80, v80, v81
	v_lshl_add_u64 v[82:83], s[48:49], 0, v[82:83]
	v_lshl_add_u64 v[82:83], s[56:57], 2, v[82:83]
	v_lshl_add_u64 v[82:83], v[82:83], 0, s[42:43]
	global_store_dword v[82:83], v80, off

; __device__ __forceinline__ float sumsq8(f32x4 a, f32x4 b) { return (a.x * a.x + a.y * a.y) + (a.z * a.z + a.w * a.w) + (b.x * b.x + b.y * b.y) + (b.z * b.z + b.w * b.w); }
.LBB0_3007:
	v_pk_mul_f32 v[68:69], v[68:69], v[68:69]
	v_pk_mul_f32 v[70:71], v[70:71], v[70:71]
	v_pk_mul_f32 v[64:65], v[64:65], v[64:65]
	v_add_f32_e32 v70, v70, v71
	v_add_f32_e32 v68, v68, v69
	v_pk_mul_f32 v[66:67], v[66:67], v[66:67]
	v_add_f32_e32 v68, v68, v70
	v_add_f32_e32 v64, v64, v65
	v_pk_mul_f32 v[76:77], v[76:77], v[76:77]
	v_pk_mul_f32 v[78:79], v[78:79], v[78:79]
	v_add_f32_e32 v64, v64, v68
	v_add_f32_e32 v65, v66, v67
	v_pk_mul_f32 v[72:73], v[72:73], v[72:73]
	v_add_f32_e32 v64, v65, v64
	v_add_f32_e32 v65, v78, v79
	v_add_f32_e32 v66, v76, v77
	v_pk_mul_f32 v[74:75], v[74:75], v[74:75]
	v_add_f32_e32 v65, v66, v65
	v_add_f32_e32 v66, v72, v73
	v_add_f32_e32 v65, v66, v65
	v_add_f32_e32 v66, v74, v75
	v_add_f32_e32 v65, v66, v65
	v_add_f32_e32 v64, v65, v64
	v_mov_b32_e32 v65, v64
	s_nop 1
	v_permlane16_swap_b32_e32 v65, v64
	s_waitcnt lgkmcnt(0)
	v_add_f32_e32 v64, v64, v65
	v_mov_b32_e32 v65, v64
	s_nop 1
	v_permlane32_swap_b32_e32 v65, v64
	s_and_saveexec_b64 s[46:47], s[28:29]
	s_cbranch_execz .LBB0_3009
	v_readlane_b32 s48, v254, 8
	v_lshlrev_b64 v[66:67], 6, v[80:81]
	v_readlane_b32 s49, v254, 9
	s_lshl_b32 s42, s18, 2
	s_waitcnt lgkmcnt(0)
	v_add_f32_e32 v64, v64, v65
	v_lshl_add_u64 v[66:67], s[48:49], 0, v[66:67]
	v_lshl_add_u64 v[66:67], s[56:57], 2, v[66:67]
	v_lshl_add_u64 v[66:67], v[66:67], 0, s[42:43]
	global_store_dword v[66:67], v64, off

; __device__ __forceinline__ float sumsq8(f32x4 a, f32x4 b) { return (a.x * a.x + a.y * a.y) + (a.z * a.z + a.w * a.w) + (b.x * b.x + b.y * b.y) + (b.z * b.z + b.w * b.w); }
.LBB0_3017:
	v_pk_mul_f32 v[52:53], v[52:53], v[52:53]
	v_pk_mul_f32 v[54:55], v[54:55], v[54:55]
	v_pk_mul_f32 v[48:49], v[48:49], v[48:49]
	v_add_f32_e32 v54, v54, v55
	v_add_f32_e32 v52, v52, v53
	v_pk_mul_f32 v[50:51], v[50:51], v[50:51]
	v_add_f32_e32 v52, v52, v54
	v_add_f32_e32 v48, v48, v49
	v_pk_mul_f32 v[60:61], v[60:61], v[60:61]
	v_pk_mul_f32 v[62:63], v[62:63], v[62:63]
	v_add_f32_e32 v48, v48, v52
	v_add_f32_e32 v49, v50, v51
	v_pk_mul_f32 v[56:57], v[56:57], v[56:57]
	v_add_f32_e32 v48, v49, v48
	v_add_f32_e32 v49, v62, v63
	v_add_f32_e32 v50, v60, v61
	v_pk_mul_f32 v[58:59], v[58:59], v[58:59]
	v_add_f32_e32 v49, v50, v49
	v_add_f32_e32 v50, v56, v57
	v_add_f32_e32 v49, v50, v49
	v_add_f32_e32 v50, v58, v59
	v_add_f32_e32 v49, v50, v49
	v_add_f32_e32 v48, v49, v48
	v_mov_b32_e32 v49, v48
	s_nop 1
	v_permlane16_swap_b32_e32 v49, v48
	s_waitcnt lgkmcnt(0)
	v_add_f32_e32 v48, v48, v49
	v_mov_b32_e32 v49, v48
	s_nop 1
	v_permlane32_swap_b32_e32 v49, v48
	s_and_saveexec_b64 s[46:47], s[28:29]
	s_cbranch_execz .LBB0_3019
	v_readlane_b32 s48, v254, 8
	v_lshlrev_b64 v[50:51], 6, v[64:65]
	v_readlane_b32 s49, v254, 9
	s_lshl_b32 s42, s18, 2
	s_waitcnt lgkmcnt(0)
	v_add_f32_e32 v48, v48, v49
	v_lshl_add_u64 v[50:51], s[48:49], 0, v[50:51]
	v_lshl_add_u64 v[50:51], s[56:57], 2, v[50:51]
	v_lshl_add_u64 v[50:51], v[50:51], 0, s[42:43]
	global_store_dword v[50:51], v48, off

; __device__ __forceinline__ float sumsq8(f32x4 a, f32x4 b) { return (a.x * a.x + a.y * a.y) + (a.z * a.z + a.w * a.w) + (b.x * b.x + b.y * b.y) + (b.z * b.z + b.w * b.w); }
.LBB0_3027:
	v_pk_mul_f32 v[36:37], v[36:37], v[36:37]
	v_pk_mul_f32 v[38:39], v[38:39], v[38:39]
	v_pk_mul_f32 v[32:33], v[32:33], v[32:33]
	v_add_f32_e32 v38, v38, v39
	v_add_f32_e32 v36, v36, v37
	v_pk_mul_f32 v[34:35], v[34:35], v[34:35]
	v_add_f32_e32 v36, v36, v38
	v_add_f32_e32 v32, v32, v33
	v_pk_mul_f32 v[44:45], v[44:45], v[44:45]
	v_pk_mul_f32 v[46:47], v[46:47], v[46:47]
	v_add_f32_e32 v32, v32, v36
	v_add_f32_e32 v33, v34, v35
	v_pk_mul_f32 v[40:41], v[40:41], v[40:41]
	v_add_f32_e32 v32, v33, v32
	v_add_f32_e32 v33, v46, v47
	v_add_f32_e32 v34, v44, v45
	v_pk_mul_f32 v[42:43], v[42:43], v[42:43]
	v_add_f32_e32 v33, v34, v33
	v_add_f32_e32 v34, v40, v41
	v_add_f32_e32 v33, v34, v33
	v_add_f32_e32 v34, v42, v43
	v_add_f32_e32 v33, v34, v33
	v_add_f32_e32 v32, v33, v32
	v_mov_b32_e32 v33, v32
	s_nop 1
	v_permlane16_swap_b32_e32 v33, v32
	s_waitcnt lgkmcnt(0)
	v_add_f32_e32 v32, v32, v33
	v_mov_b32_e32 v33, v32
	s_nop 1
	v_permlane32_swap_b32_e32 v33, v32
	s_and_saveexec_b64 s[46:47], s[28:29]
	s_cbranch_execz .LBB0_3029
	v_readlane_b32 s48, v254, 8
	v_lshlrev_b64 v[34:35], 6, v[48:49]
	v_readlane_b32 s49, v254, 9
	s_lshl_b32 s42, s18, 2
	s_waitcnt lgkmcnt(0)
	v_add_f32_e32 v32, v32, v33
	v_lshl_add_u64 v[34:35], s[48:49], 0, v[34:35]
	v_lshl_add_u64 v[34:35], s[56:57], 2, v[34:35]
	v_lshl_add_u64 v[34:35], v[34:35], 0, s[42:43]
	global_store_dword v[34:35], v32, off

; __device__ __forceinline__ float sumsq8(f32x4 a, f32x4 b) { return (a.x * a.x + a.y * a.y) + (a.z * a.z + a.w * a.w) + (b.x * b.x + b.y * b.y) + (b.z * b.z + b.w * b.w); }
.LBB0_3037:
	v_pk_mul_f32 v[20:21], v[20:21], v[20:21]
	v_pk_mul_f32 v[22:23], v[22:23], v[22:23]
	v_pk_mul_f32 v[16:17], v[16:17], v[16:17]
	v_add_f32_e32 v22, v22, v23
	v_add_f32_e32 v20, v20, v21
	v_pk_mul_f32 v[18:19], v[18:19], v[18:19]
	v_add_f32_e32 v20, v20, v22
	v_add_f32_e32 v16, v16, v17
	v_pk_mul_f32 v[28:29], v[28:29], v[28:29]
	v_pk_mul_f32 v[30:31], v[30:31], v[30:31]
	v_add_f32_e32 v16, v16, v20
	v_add_f32_e32 v17, v18, v19
	v_pk_mul_f32 v[24:25], v[24:25], v[24:25]
	v_add_f32_e32 v16, v17, v16
	v_add_f32_e32 v17, v30, v31
	v_add_f32_e32 v18, v28, v29
	v_pk_mul_f32 v[26:27], v[26:27], v[26:27]
	v_add_f32_e32 v17, v18, v17
	v_add_f32_e32 v18, v24, v25
	v_add_f32_e32 v17, v18, v17
	v_add_f32_e32 v18, v26, v27
	v_add_f32_e32 v17, v18, v17
	v_add_f32_e32 v16, v17, v16
	v_mov_b32_e32 v17, v16
	s_nop 1
	v_permlane16_swap_b32_e32 v17, v16
	s_waitcnt lgkmcnt(0)
	v_add_f32_e32 v16, v16, v17
	v_mov_b32_e32 v17, v16
	s_nop 1
	v_permlane32_swap_b32_e32 v17, v16
	s_and_saveexec_b64 s[46:47], s[28:29]
	s_cbranch_execz .LBB0_3039
	v_readlane_b32 s48, v254, 8
	v_lshlrev_b64 v[18:19], 6, v[32:33]
	v_readlane_b32 s49, v254, 9
	s_lshl_b32 s42, s18, 2
	s_waitcnt lgkmcnt(0)
	v_add_f32_e32 v16, v16, v17
	v_lshl_add_u64 v[18:19], s[48:49], 0, v[18:19]
	v_lshl_add_u64 v[18:19], s[56:57], 2, v[18:19]
	v_lshl_add_u64 v[18:19], v[18:19], 0, s[42:43]
	global_store_dword v[18:19], v16, off

; __device__ __forceinline__ float sumsq8(f32x4 a, f32x4 b) { return (a.x * a.x + a.y * a.y) + (a.z * a.z + a.w * a.w) + (b.x * b.x + b.y * b.y) + (b.z * b.z + b.w * b.w); }
.LBB0_3047:
	v_pk_mul_f32 v[4:5], v[4:5], v[4:5]
	v_pk_mul_f32 v[6:7], v[6:7], v[6:7]
	v_pk_mul_f32 v[0:1], v[0:1], v[0:1]
	v_add_f32_e32 v6, v6, v7
	v_add_f32_e32 v4, v4, v5
	v_pk_mul_f32 v[2:3], v[2:3], v[2:3]
	v_add_f32_e32 v4, v4, v6
	v_add_f32_e32 v0, v0, v1
	v_pk_mul_f32 v[12:13], v[12:13], v[12:13]
	v_pk_mul_f32 v[14:15], v[14:15], v[14:15]
	v_add_f32_e32 v0, v0, v4
	v_add_f32_e32 v1, v2, v3
	v_pk_mul_f32 v[8:9], v[8:9], v[8:9]
	v_add_f32_e32 v0, v1, v0
	v_add_f32_e32 v1, v14, v15
	v_add_f32_e32 v2, v12, v13
	v_pk_mul_f32 v[10:11], v[10:11], v[10:11]
	v_add_f32_e32 v1, v2, v1
	v_add_f32_e32 v2, v8, v9
	v_add_f32_e32 v1, v2, v1
	v_add_f32_e32 v2, v10, v11
	v_add_f32_e32 v1, v2, v1
	v_add_f32_e32 v0, v1, v0
	v_mov_b32_e32 v1, v0
	s_nop 1
	v_permlane16_swap_b32_e32 v1, v0
	s_waitcnt lgkmcnt(0)
	v_add_f32_e32 v0, v0, v1
	v_mov_b32_e32 v1, v0
	s_nop 1
	v_permlane32_swap_b32_e32 v1, v0
	s_and_saveexec_b64 s[4:5], s[28:29]
	s_cbranch_execz .LBB0_3049
	v_readlane_b32 s6, v254, 8
	v_lshlrev_b64 v[2:3], 6, v[16:17]
	v_readlane_b32 s7, v254, 9
	s_lshl_b32 s42, s18, 2
	s_waitcnt lgkmcnt(0)
	v_add_f32_e32 v0, v0, v1
	v_lshl_add_u64 v[2:3], s[6:7], 0, v[2:3]
	v_lshl_add_u64 v[2:3], s[56:57], 2, v[2:3]
	v_lshl_add_u64 v[2:3], v[2:3], 0, s[42:43]
	global_store_dword v[2:3], v0, off
